# mixer inter-chunk MFMA section: LDS fragment reads software-pipelined through a 12-buffer register ring (was read-wait-mfma serialized)
# speedup vs baseline: 1.0055x; 1.0055x over previous
; #define LAS __attribute__((address_space(3)))
; __device__ __forceinline__ f32x4 mfma16(bf16x8 a, bf16x8 b, f32x4 c) { return __builtin_amdgcn_mfma_f32_16x16x32_bf16(a, b, c, 0, 0, 0); }
; __device__ __forceinline__ void mixer_phase(LAS unsigned char* lds, const bf16_t* __restrict__ QKc, const bf16_t* __restrict__ PROJ, bf16_t* HOUT, const float* __restrict__ DEN, const float* __restrict__ GS, int vcu, int G) {
;     ...
;             const float dec = vb[512];
; #pragma unroll
;             for (int p = 0; p < 2; ++p)
; #pragma unroll
;                 for (int et = 0; et < 3; ++et) accC[p][et] = accC[p][et] * dec;
;             f32x4 accO[3];
; #pragma unroll
;             for (int et = 0; et < 3; ++et) accO[et] = (f32x4){0.f, 0.f, 0.f, 0.f};
; #pragma unroll
;             for (int p = 0; p < 2; ++p) {
;                 const int KSB = p ? MX_KS1 : MX_KS0;
; #pragma unroll
;                 for (int ks = 0; ks < 4; ++ks)
; #pragma unroll
;                     for (int et = 0; et < 3; ++et) { const bf16x8 a = *(const LAS bf16x8*)(lds + MX_CT + (16 * et + l15) * 528 + (128 * p + 32 * ks + 8 * quad) * 2); accO[et] = mfma16(a, qf[4 * p + ks], accO[et]); }
; #pragma unroll
;                 for (int k4 = 0; k4 < 4; ++k4) {
;                     const bf16x8 a = *(const LAS bf16x8*)(lds + KSB + (16 * w + l15) * 272 + (((4 * k4 + quad) ^ ((2 * w + (l15 >> 3)) & 15)) * 16));
; #pragma unroll
;                     for (int et = 0; et < 3; ++et) { const bf16x8 bb = *(const LAS bf16x8*)(lds + MX_VTW + (16 * et + l15) * 272 + (32 * k4 + 8 * quad) * 2); accC[p][et] = mfma16(a, bb, accC[p][et]); }
;                 }
;             }
.LBB0_524:
	s_or_b64 exec, exec, s[0:1]
	v_mov_b32_e32 v52, s51
	ds_read_b32 v60, v52 offset:2048
	ds_read_b128 v[72:75], v195 offset:8448
	ds_read_b128 v[76:79], v195
	ds_read_b128 v[84:87], v195 offset:16896
	ds_read_b128 v[210:213], v196
	ds_read_b128 v[220:223], v196 offset:8448
	ds_read_b128 v[224:227], v196 offset:16896
	ds_read_b128 v[228:231], v197
	ds_read_b128 v[232:235], v197 offset:8448
	ds_read_b128 v[236:239], v197 offset:16896
	ds_read_b128 v[240:243], v198
	ds_read_b128 v[248:251], v198 offset:8448
	ds_read_b128 v[252:255], v198 offset:16896
	s_waitcnt lgkmcnt(12)
	v_pk_mul_f32 v[46:47], v[46:47], v[60:61] op_sel_hi:[1,0]
	v_pk_mul_f32 v[44:45], v[44:45], v[60:61] op_sel_hi:[1,0]
	v_pk_mul_f32 v[42:43], v[42:43], v[60:61] op_sel_hi:[1,0]
	v_mul_f32_e64 v40, v40, v60
	v_mul_f32_e64 v41, v41, v60
	v_pk_mul_f32 v[38:39], v[38:39], v[60:61] op_sel_hi:[1,0]
	v_pk_mul_f32 v[36:37], v[36:37], v[60:61] op_sel_hi:[1,0]
	v_mul_f32_e64 v54, v94, v60
	v_mul_f32_e64 v55, v95, v60
	v_pk_mul_f32 v[52:53], v[92:93], v[60:61] op_sel_hi:[1,0]
	v_pk_mul_f32 v[58:59], v[90:91], v[60:61] op_sel_hi:[1,0]
	v_pk_mul_f32 v[56:57], v[88:89], v[60:61] op_sel_hi:[1,0]
	v_pk_mul_f32 v[62:63], v[82:83], v[60:61] op_sel_hi:[1,0]
	v_pk_mul_f32 v[60:61], v[80:81], v[60:61] op_sel_hi:[1,0]
	s_waitcnt lgkmcnt(11)
	v_mfma_f32_16x16x32_bf16 v[68:71], v[72:75], v[32:35], 0
	ds_read_b128 v[72:75], v184
	s_waitcnt lgkmcnt(11)
	v_mfma_f32_16x16x32_bf16 v[64:67], v[76:79], v[32:35], 0
	ds_read_b128 v[76:79], v185
	s_waitcnt lgkmcnt(11)
	v_mfma_f32_16x16x32_bf16 v[32:35], v[84:87], v[32:35], 0
	ds_read_b128 v[84:87], v185 offset:4352
	s_waitcnt lgkmcnt(11)
	v_mfma_f32_16x16x32_bf16 v[64:67], v[210:213], v[28:31], v[64:67]
	ds_read_b128 v[210:213], v185 offset:8704
	s_waitcnt lgkmcnt(11)
	v_mfma_f32_16x16x32_bf16 v[68:71], v[220:223], v[28:31], v[68:71]
	ds_read_b128 v[220:223], v186
	s_waitcnt lgkmcnt(11)
	v_mfma_f32_16x16x32_bf16 v[28:31], v[224:227], v[28:31], v[32:35]
	ds_read_b128 v[224:227], v185 offset:64
	s_waitcnt lgkmcnt(11)
	v_mfma_f32_16x16x32_bf16 v[32:35], v[228:231], v[24:27], v[64:67]
	ds_read_b128 v[228:231], v185 offset:4416
	s_waitcnt lgkmcnt(11)
	v_mfma_f32_16x16x32_bf16 v[64:67], v[232:235], v[24:27], v[68:71]
	ds_read_b128 v[232:235], v185 offset:8768
	s_waitcnt lgkmcnt(11)
	v_mfma_f32_16x16x32_bf16 v[24:27], v[236:239], v[24:27], v[28:31]
	ds_read_b128 v[236:239], v187
	s_waitcnt lgkmcnt(11)
	v_mfma_f32_16x16x32_bf16 v[96:99], v[240:243], v[20:23], v[32:35]
	ds_read_b128 v[240:243], v185 offset:128
	s_waitcnt lgkmcnt(11)
	v_mfma_f32_16x16x32_bf16 v[100:103], v[248:251], v[20:23], v[64:67]
	ds_read_b128 v[248:251], v185 offset:4480
	s_waitcnt lgkmcnt(11)
	v_mfma_f32_16x16x32_bf16 v[104:107], v[252:255], v[20:23], v[24:27]
	ds_read_b128 v[252:255], v185 offset:8832
	s_waitcnt lgkmcnt(10)
	v_mfma_f32_16x16x32_bf16 v[24:27], v[72:75], v[76:79], v[44:47]
	s_waitcnt lgkmcnt(9)
	v_mfma_f32_16x16x32_bf16 v[28:31], v[72:75], v[84:87], v[40:43]
	s_waitcnt lgkmcnt(8)
	v_mfma_f32_16x16x32_bf16 v[20:23], v[72:75], v[210:213], v[36:39]
	ds_read_b128 v[72:75], v188
	ds_read_b128 v[76:79], v185 offset:192
	ds_read_b128 v[84:87], v185 offset:4544
	ds_read_b128 v[210:213], v185 offset:8896
	s_waitcnt lgkmcnt(10)
	v_mfma_f32_16x16x32_bf16 v[24:27], v[220:223], v[224:227], v[24:27]
	s_waitcnt lgkmcnt(9)
	v_mfma_f32_16x16x32_bf16 v[28:31], v[220:223], v[228:231], v[28:31]
	s_waitcnt lgkmcnt(8)
	v_mfma_f32_16x16x32_bf16 v[20:23], v[220:223], v[232:235], v[20:23]
	ds_read_b128 v[220:223], v199
	ds_read_b128 v[224:227], v199 offset:8448
	ds_read_b128 v[228:231], v199 offset:16896
	ds_read_b128 v[232:235], v200
	s_waitcnt lgkmcnt(10)
	v_mfma_f32_16x16x32_bf16 v[24:27], v[236:239], v[240:243], v[24:27]
	s_waitcnt lgkmcnt(9)
	v_mfma_f32_16x16x32_bf16 v[28:31], v[236:239], v[248:251], v[28:31]
	s_waitcnt lgkmcnt(8)
	v_mfma_f32_16x16x32_bf16 v[36:39], v[236:239], v[252:255], v[20:23]
	ds_read_b128 v[236:239], v200 offset:8448
	ds_read_b128 v[240:243], v200 offset:16896
	ds_read_b128 v[248:251], v201
	ds_read_b128 v[252:255], v201 offset:8448
	s_waitcnt lgkmcnt(10)
	v_mfma_f32_16x16x32_bf16 v[44:47], v[72:75], v[76:79], v[24:27]
	s_waitcnt lgkmcnt(9)
	v_mfma_f32_16x16x32_bf16 v[40:43], v[72:75], v[84:87], v[28:31]
	s_waitcnt lgkmcnt(8)
	v_mfma_f32_16x16x32_bf16 v[36:39], v[72:75], v[210:213], v[36:39]
	ds_read_b128 v[72:75], v201 offset:16896
	ds_read_b128 v[76:79], v202
	ds_read_b128 v[84:87], v202 offset:8448
	ds_read_b128 v[210:213], v202 offset:16896
	s_waitcnt lgkmcnt(11)
	v_mfma_f32_16x16x32_bf16 v[96:99], v[220:223], v[16:19], v[96:99]
	ds_read_b128 v[220:223], v184 offset:34816
	s_waitcnt lgkmcnt(11)
	v_mfma_f32_16x16x32_bf16 v[100:103], v[224:227], v[16:19], v[100:103]
	ds_read_b128 v[224:227], v185
	s_waitcnt lgkmcnt(11)
	v_mfma_f32_16x16x32_bf16 v[16:19], v[228:231], v[16:19], v[104:107]
	ds_read_b128 v[228:231], v185 offset:4352
	s_waitcnt lgkmcnt(11)
	v_mfma_f32_16x16x32_bf16 v[96:99], v[232:235], v[12:15], v[96:99]
	ds_read_b128 v[232:235], v185 offset:8704
	s_waitcnt lgkmcnt(11)
	v_mfma_f32_16x16x32_bf16 v[100:103], v[236:239], v[12:15], v[100:103]
	ds_read_b128 v[236:239], v186 offset:34816
	s_waitcnt lgkmcnt(11)
	v_mfma_f32_16x16x32_bf16 v[12:15], v[240:243], v[12:15], v[16:19]
	ds_read_b128 v[240:243], v185 offset:64
	s_waitcnt lgkmcnt(11)
; #define LAS __attribute__((address_space(3)))
; __device__ __forceinline__ f32x4 mfma16(bf16x8 a, bf16x8 b, f32x4 c) { return __builtin_amdgcn_mfma_f32_16x16x32_bf16(a, b, c, 0, 0, 0); }
; __device__ __forceinline__ void mixer_phase(LAS unsigned char* lds, const bf16_t* __restrict__ QKc, const bf16_t* __restrict__ PROJ, bf16_t* HOUT, const float* __restrict__ DEN, const float* __restrict__ GS, int vcu, int G) {
;     ...
;         float sb_b = 0.f, sb_u = 0.f, sb_pm = 0.f, sb_pmall = 0.f;
;     ...
; #pragma unroll
;             for (int p = 0; p < 2; ++p) {
;                 const int KSB = p ? MX_KS1 : MX_KS0;
; #pragma unroll
;                 for (int ks = 0; ks < 4; ++ks)
; #pragma unroll
;                     for (int et = 0; et < 3; ++et) { const bf16x8 a = *(const LAS bf16x8*)(lds + MX_CT + (16 * et + l15) * 528 + (128 * p + 32 * ks + 8 * quad) * 2); accO[et] = mfma16(a, qf[4 * p + ks], accO[et]); }
; #pragma unroll
;                 for (int k4 = 0; k4 < 4; ++k4) {
;                     const bf16x8 a = *(const LAS bf16x8*)(lds + KSB + (16 * w + l15) * 272 + (((4 * k4 + quad) ^ ((2 * w + (l15 >> 3)) & 15)) * 16));
; #pragma unroll
;                     for (int et = 0; et < 3; ++et) { const bf16x8 bb = *(const LAS bf16x8*)(lds + MX_VTW + (16 * et + l15) * 272 + (32 * k4 + 8 * quad) * 2); accC[p][et] = mfma16(a, bb, accC[p][et]); }
;                 }
;             }
;             if (c < 31) { MX_LOAD(c + 1); MX_SB_CALC(c + 1); }
	v_mfma_f32_16x16x32_bf16 v[16:19], v[248:251], v[8:11], v[96:99]
	ds_read_b128 v[248:251], v185 offset:4416
	s_waitcnt lgkmcnt(11)
	v_mfma_f32_16x16x32_bf16 v[96:99], v[252:255], v[8:11], v[100:103]
	ds_read_b128 v[252:255], v185 offset:8768
	s_waitcnt lgkmcnt(11)
	v_mfma_f32_16x16x32_bf16 v[8:11], v[72:75], v[8:11], v[12:15]
	ds_read_b128 v[72:75], v187 offset:34816
	s_waitcnt lgkmcnt(11)
	v_mfma_f32_16x16x32_bf16 v[100:103], v[76:79], v[4:7], v[16:19]
	ds_read_b128 v[76:79], v185 offset:128
	s_waitcnt lgkmcnt(11)
	v_mfma_f32_16x16x32_bf16 v[96:99], v[84:87], v[4:7], v[96:99]
	ds_read_b128 v[84:87], v185 offset:4480
	s_waitcnt lgkmcnt(11)
	v_mfma_f32_16x16x32_bf16 v[104:107], v[210:213], v[4:7], v[8:11]
	ds_read_b128 v[210:213], v185 offset:8832
	s_waitcnt lgkmcnt(10)
	v_mfma_f32_16x16x32_bf16 v[8:11], v[220:223], v[224:227], v[52:55]
	s_waitcnt lgkmcnt(9)
	v_mfma_f32_16x16x32_bf16 v[12:15], v[220:223], v[228:231], v[56:59]
	s_waitcnt lgkmcnt(8)
	v_mfma_f32_16x16x32_bf16 v[4:7], v[220:223], v[232:235], v[60:63]
	ds_read_b128 v[220:223], v188 offset:34816
	ds_read_b128 v[224:227], v185 offset:8896
	ds_read_b128 v[228:231], v185 offset:192
	ds_read_b128 v[232:235], v185 offset:4544
	s_waitcnt lgkmcnt(10)
	v_mfma_f32_16x16x32_bf16 v[8:11], v[236:239], v[240:243], v[8:11]
	s_waitcnt lgkmcnt(9)
	v_mfma_f32_16x16x32_bf16 v[12:15], v[236:239], v[248:251], v[12:15]
	s_waitcnt lgkmcnt(8)
	v_mfma_f32_16x16x32_bf16 v[4:7], v[236:239], v[252:255], v[4:7]
	s_waitcnt lgkmcnt(6)
	v_mfma_f32_16x16x32_bf16 v[8:11], v[72:75], v[76:79], v[8:11]
	s_waitcnt lgkmcnt(5)
	v_mfma_f32_16x16x32_bf16 v[12:15], v[72:75], v[84:87], v[12:15]
	s_waitcnt lgkmcnt(4)
	v_mfma_f32_16x16x32_bf16 v[4:7], v[72:75], v[210:213], v[4:7]
	s_waitcnt lgkmcnt(2)
	v_mfma_f32_16x16x32_bf16 v[80:83], v[220:223], v[224:227], v[4:7]
	s_waitcnt lgkmcnt(1)
	v_mfma_f32_16x16x32_bf16 v[92:95], v[220:223], v[228:231], v[8:11]
	s_waitcnt lgkmcnt(0)
	v_mfma_f32_16x16x32_bf16 v[88:91], v[220:223], v[232:235], v[12:15]
	s_mov_b32 s0, 0x100000
	v_lshl_add_u64 v[106:107], v[150:151], 0, s[30:31]
	v_lshl_add_u64 v[76:77], v[152:153], 0, s[30:31]
	s_nop 1
	v_add_co_u32_e32 v52, vcc, s0, v76
	s_mov_b32 s0, 0x102000
	s_nop 1
	v_addc_co_u32_e32 v53, vcc, 0, v77, vcc
	v_add_co_u32_e32 v60, vcc, s0, v76
	s_mov_b32 s0, 0x104000
	s_nop 1
	v_addc_co_u32_e32 v61, vcc, 0, v77, vcc
	v_add_co_u32_e32 v68, vcc, s0, v76
	s_mov_b32 s0, 0x106000
	s_nop 1
	v_addc_co_u32_e32 v69, vcc, 0, v77, vcc
	v_add_co_u32_e32 v76, vcc, s0, v76
	s_nop 1
	v_addc_co_u32_e32 v77, vcc, 0, v77, vcc
	v_add_co_u32_e32 v210, vcc, s77, v106
	v_lshl_add_u64 v[4:5], v[154:155], 0, s[30:31]
	s_nop 0
	v_addc_co_u32_e32 v211, vcc, 0, v107, vcc
	global_load_dwordx4 v[32:35], v[4:5], off offset:-256
	global_load_dwordx4 v[28:31], v[4:5], off offset:-192
	global_load_dwordx4 v[24:27], v[4:5], off offset:-128
	global_load_dwordx4 v[20:23], v[4:5], off offset:-64
	global_load_dwordx4 v[16:19], v[4:5], off
	global_load_dwordx4 v[12:15], v[4:5], off offset:64
	global_load_dwordx4 v[8:11], v[4:5], off offset:128
	s_nop 0
	global_load_dwordx4 v[4:7], v[4:5], off offset:192
	s_nop 0
	global_load_dwordx4 v[56:59], v[52:53], off offset:2048
	s_nop 0
	global_load_dwordx4 v[52:55], v[52:53], off offset:2304
	s_nop 0
	global_load_dwordx4 v[64:67], v[60:61], off offset:2048
	s_nop 0
	global_load_dwordx4 v[60:63], v[60:61], off offset:2304
	s_nop 0
	global_load_dwordx4 v[72:75], v[68:69], off offset:2048
	s_nop 0
	global_load_dwordx4 v[68:71], v[68:69], off offset:2304
	s_nop 0
	global_load_dwordx4 v[84:87], v[76:77], off offset:2048
	s_nop 0
	global_load_dwordx4 v[76:79], v[76:77], off offset:2304
	s_nop 0
	global_load_dword v105, v[210:211], off
	v_add_co_u32_e32 v210, vcc, 0x11284000, v106
	s_nop 1
	v_addc_co_u32_e32 v211, vcc, 0, v107, vcc
	global_load_dword v209, v[210:211], off
	v_add_co_u32_e32 v210, vcc, 0x11288000, v106
	s_nop 1
	v_addc_co_u32_e32 v211, vcc, 0, v107, vcc
	v_add_co_u32_e32 v106, vcc, 0x1128c000, v106
	global_load_dword v210, v[210:211], off
	s_nop 0
	v_addc_co_u32_e32 v107, vcc, 0, v107, vcc
	global_load_dword v211, v[106:107], off
	s_and_saveexec_b64 s[0:1], s[44:45]
	s_cbranch_execz .LBB0_527
	v_mov_b32_e32 v106, s88
	ds_read_b32 v106, v106
	s_waitcnt vmcnt(21)
	v_max_f32_e32 v107, v203, v203
	s_cmp_eq_u32 s50, 1
	s_cselect_b32 s50, 0x820, 0
	s_add_i32 s50, s50, 0
	s_waitcnt lgkmcnt(0)
	v_max_f32_e32 v159, v106, v106
	v_max_f32_e32 v212, v159, v107
	s_waitcnt vmcnt(20)
	v_max_f32_e32 v107, v143, v143
	v_sub_f32_e32 v214, v106, v212
	v_max_f32_e32 v107, v159, v107
	v_sub_f32_e32 v159, v203, v212
	v_mul_f32_e32 v214, 0x3fb8aa3b, v214
	v_mul_f32_e32 v159, 0x3fb8aa3b, v159
	v_exp_f32_e32 v214, v214
	v_exp_f32_e32 v159, v159
	s_add_i32 s50, s50, 0x1a600
	v_lshl_add_u32 v213, v108, 2, s50
	v_mul_f32_e32 v214, 0x3d800000, v214
	ds_write2st64_b32 v213, v159, v214 offset1:2
	v_add_f32_e32 v159, v139, v212
	v_sub_f32_e32 v212, v141, v107
	v_mul_f32_e32 v159, 0xbfb8aa3b, v159
	v_mul_f32_e32 v212, 0x3fb8aa3b, v212
	v_exp_f32_e32 v159, v159
	v_exp_f32_e32 v212, v212
	ds_write2st64_b32 v213, v159, v212 offset0:4 offset1:6
	s_and_b64 exec, exec, s[10:11]
	s_cbranch_execz .LBB0_527
	v_sub_f32_e32 v106, v106, v107
	v_mul_f32_e32 v106, 0x3fb8aa3b, v106
	v_exp_f32_e32 v106, v106
	v_mov_b32_e32 v107, s50
	ds_write_b32 v107, v106 offset:2048
